# forget-logit tile: padding weight rows 32..127 no longer fetched/staged; waves of the all-padding column half skip LDS reads and MFMAs
# speedup vs baseline: 1.0216x; 1.0065x over previous
.LBB0_233:
	s_cmp_eq_u32 s52, 2
	s_cbranch_scc0 .LBB0_257
	v_readfirstlane_b32 s98, v204
	s_lshr_b32 s98, s98, 7
	s_ashr_i32 s77, s76, 31
	s_lshl_b64 s[4:5], s[76:77], 18
	s_ashr_i32 s75, s74, 31
	v_lshl_add_u64 v[0:1], v[154:155], 0, s[4:5]
	s_lshl_b64 s[6:7], s[74:75], 18
	v_add_co_u32_e32 v4, vcc, 0x10000, v0
	v_lshl_add_u64 v[2:3], v[156:157], 0, s[6:7]
	s_nop 0
	v_addc_co_u32_e32 v5, vcc, 0, v1, vcc
	v_add_co_u32_e32 v6, vcc, 0x10000, v2
	global_load_dwordx4 v[24:27], v[0:1], off
	global_load_dwordx4 v[28:31], v[2:3], off
	v_addc_co_u32_e32 v7, vcc, 0, v3, vcc
	v_add_co_u32_e32 v8, vcc, 0x20000, v0
	global_load_dwordx4 v[68:71], v[4:5], off
	v_addc_co_u32_e32 v9, vcc, 0, v1, vcc
	v_add_co_u32_e32 v10, vcc, 0x20000, v2
	global_load_dwordx4 v[76:79], v[8:9], off
	s_nop 0
	v_addc_co_u32_e32 v11, vcc, 0, v3, vcc
	v_add_co_u32_e32 v12, vcc, 0x30000, v0
	s_nop 0
	v_addc_co_u32_e32 v13, vcc, 0, v1, vcc
	global_load_dwordx4 v[84:87], v[12:13], off
	v_add_co_u32_e32 v14, vcc, 0x30000, v2
	s_mov_b32 s34, 0
	s_nop 0
	v_addc_co_u32_e32 v15, vcc, 0, v3, vcc
	global_load_dwordx4 v[32:35], v[0:1], off offset:128
	global_load_dwordx4 v[36:39], v[2:3], off offset:128
	global_load_dwordx4 v[40:43], v[4:5], off offset:128
	global_load_dwordx4 v[48:51], v[8:9], off offset:128
	global_load_dwordx4 v[56:59], v[12:13], off offset:128
	v_mov_b32_e32 v0, 0
	s_mov_b64 s[0:1], 0
	v_mov_b32_e32 v1, v0
	v_mov_b32_e32 v2, v0
	v_mov_b32_e32 v3, v0
	v_mov_b32_e32 v4, v0
	v_mov_b32_e32 v5, v0
	v_mov_b32_e32 v6, v0
	v_mov_b32_e32 v7, v0
	v_mov_b32_e32 v8, v0
	v_mov_b32_e32 v9, v0
	v_mov_b32_e32 v10, v0
	v_mov_b32_e32 v11, v0
	v_mov_b32_e32 v12, v0
	v_mov_b32_e32 v13, v0
	v_mov_b32_e32 v14, v0
	v_mov_b32_e32 v15, v0
	v_mov_b32_e32 v16, v0
	v_mov_b32_e32 v17, v0
	v_mov_b32_e32 v18, v0
	v_mov_b32_e32 v19, v0
	v_mov_b32_e32 v20, v0
	v_mov_b32_e32 v21, v0
	v_mov_b32_e32 v22, v0
	v_mov_b32_e32 v23, v0
	v_lshl_add_u64 v[64:65], v[166:167], 0, s[6:7]
	v_lshl_add_u64 v[66:67], v[166:167], 0, s[4:5]
	s_waitcnt vmcnt(9)
	ds_write_b128 v178, v[24:27]
	s_waitcnt vmcnt(8)
	ds_write_b128 v178, v[28:31] offset:18432
	s_waitcnt vmcnt(7)
	ds_write_b128 v178, v[68:71] offset:4608
	s_nop 0
	s_waitcnt vmcnt(6)
	ds_write_b128 v178, v[76:79] offset:9216
	s_nop 0
	s_waitcnt vmcnt(5)
	ds_write_b128 v178, v[84:87] offset:13824
	s_nop 0
	v_mov_b32_e32 v24, v0
	v_mov_b32_e32 v25, v0
	v_mov_b32_e32 v26, v0
	v_mov_b32_e32 v27, v0
	v_mov_b32_e32 v28, v0
	v_mov_b32_e32 v29, v0
	v_mov_b32_e32 v30, v0
	v_mov_b32_e32 v31, v0
	s_waitcnt lgkmcnt(0)
	s_barrier
	s_branch .LBB0_236

.LBB0_236:
	s_bitcmp1_b32 s34, 0
	s_cselect_b32 s4, 0x9000, 0
	s_cmp_eq_u32 s98, 1
	s_cbranch_scc1 .Lff_skip
	v_add3_u32 v88, s4, v179, v180
	ds_read_b128 v[68:71], v88
	v_add3_u32 v89, s4, v181, v180
	ds_read_b128 v[72:75], v89 offset:18432
	ds_read_b128 v[76:79], v88 offset:32
	ds_read_b128 v[80:83], v89 offset:18464
	s_waitcnt lgkmcnt(2)
	v_mfma_f32_32x32x16_bf16 v[16:31], v[68:71], v[72:75], v[16:31]
	ds_read_b128 v[68:71], v88 offset:4608
	ds_read_b128 v[84:87], v88 offset:4640
	s_waitcnt lgkmcnt(1)
	v_mfma_f32_32x32x16_bf16 v[0:15], v[68:71], v[72:75], v[0:15]
	v_mfma_f32_32x32x16_bf16 v[16:31], v[76:79], v[80:83], v[16:31]
	s_waitcnt lgkmcnt(0)
	v_mfma_f32_32x32x16_bf16 v[0:15], v[84:87], v[80:83], v[0:15]
	ds_read_b128 v[68:71], v88 offset:64
	ds_read_b128 v[72:75], v89 offset:18496
	ds_read_b128 v[76:79], v88 offset:96
	ds_read_b128 v[80:83], v89 offset:18528
	s_waitcnt lgkmcnt(2)
	v_mfma_f32_32x32x16_bf16 v[16:31], v[68:71], v[72:75], v[16:31]
	ds_read_b128 v[68:71], v88 offset:4672
	ds_read_b128 v[84:87], v88 offset:4704
	s_waitcnt lgkmcnt(1)
	v_mfma_f32_32x32x16_bf16 v[0:15], v[68:71], v[72:75], v[0:15]
	v_mfma_f32_32x32x16_bf16 v[16:31], v[76:79], v[80:83], v[16:31]
	s_waitcnt lgkmcnt(0)
	v_mfma_f32_32x32x16_bf16 v[0:15], v[84:87], v[80:83], v[0:15]
.Lff_skip:
	s_add_i32 s4, s34, 1
	s_cmpk_eq_i32 s0, 0x780
	s_cbranch_scc1 .LBB0_235
	s_bitcmp1_b32 s4, 0
	s_cselect_b32 s5, 0x9000, 0
	v_add_u32_e32 v68, s5, v178
	s_cmp_gt_u32 s34, 13
	s_waitcnt vmcnt(4)
	ds_write_b128 v68, v[32:35]
	s_waitcnt vmcnt(3)
	ds_write_b128 v68, v[36:39] offset:18432
	s_waitcnt vmcnt(2)
	ds_write_b128 v68, v[40:43] offset:4608
	s_nop 0
	s_waitcnt vmcnt(1)
	ds_write_b128 v68, v[48:51] offset:9216
	s_nop 0
	s_waitcnt vmcnt(0)
	ds_write_b128 v68, v[56:59] offset:13824
	s_nop 0
	s_cbranch_scc1 .LBB0_235
	v_lshl_add_u64 v[56:57], v[66:67], 0, s[0:1]
	v_add_co_u32_e32 v32, vcc, 0xa64000, v56
	v_lshl_add_u64 v[58:59], v[64:65], 0, s[0:1]
	s_nop 0
	v_addc_co_u32_e32 v33, vcc, 0, v57, vcc
	v_add_co_u32_e32 v36, vcc, 0x24000, v58
	s_nop 1
	v_addc_co_u32_e32 v37, vcc, 0, v59, vcc
	v_add_co_u32_e32 v40, vcc, 0xa74000, v56
	global_load_dwordx4 v[32:35], v[32:33], off offset:512
	s_nop 0
	global_load_dwordx4 v[36:39], v[36:37], off offset:512
	v_addc_co_u32_e32 v41, vcc, 0, v57, vcc
	v_add_co_u32_e32 v44, vcc, 0x34000, v58
	s_nop 1
	v_addc_co_u32_e32 v45, vcc, 0, v59, vcc
	v_add_co_u32_e32 v48, vcc, 0xa84000, v56
	global_load_dwordx4 v[40:43], v[40:41], off offset:512
	s_nop 0
	v_addc_co_u32_e32 v49, vcc, 0, v57, vcc
	v_add_co_u32_e32 v52, vcc, 0x44000, v58
	s_nop 1
	v_addc_co_u32_e32 v53, vcc, 0, v59, vcc
	v_add_co_u32_e32 v56, vcc, 0xa94000, v56
	global_load_dwordx4 v[48:51], v[48:49], off offset:512
	s_nop 0
	v_addc_co_u32_e32 v57, vcc, 0, v57, vcc
	v_add_co_u32_e32 v60, vcc, 0x54000, v58
	s_nop 1
	v_addc_co_u32_e32 v61, vcc, 0, v59, vcc
	global_load_dwordx4 v[56:59], v[56:57], off offset:512
	s_nop 0
	s_branch .LBB0_235
